# software-pipelined prep row loop (x -> bf16, ss0) on top of NA score-modifier rewrite and pipelined final-norm loop
# baseline (speedup 1.0000x reference)
; #define GAS __attribute__((address_space(1)))
; __device__ __forceinline__ unsigned cvt_pk_bf16(float lo, float hi) { unsigned r; asm volatile("v_cvt_pk_bf16_f32 %0, %1, %2" : "=v"(r) : "v"(lo), "v"(hi)); return r; }
; __global__ void __launch_bounds__(NTHREADS, 2) mk_fwd(Args args) {
;     ...
;         for (int row = gw; row < MT; row += ngw) {
;             const GAS f32x4* xr = (const GAS f32x4*)(x + (size_t)row * DM) + lane; u32x2* xo = (u32x2*)(R1 + (size_t)row * DM) + lane;
;             float s = 0.f; f32x4 xv[8];
; #pragma unroll
;             for (int j = 0; j < 8; ++j) { xv[j] = xr[64 * j]; s += (xv[j][0] * xv[j][0] + xv[j][1] * xv[j][1]) + (xv[j][2] * xv[j][2] + xv[j][3] * xv[j][3]); }
;             s = wave_sum(s);
;             const float rs0 = __builtin_amdgcn_rsqf(s * (1.0f / DM) + RMS_EPS);
; #pragma unroll
;             for (int j = 0; j < 8; ++j) { const f32x4 v = xv[j] * rs0; u32x2 w; w.x = cvt_pk_bf16(v[0], v[1]); w.y = cvt_pk_bf16(v[2], v[3]); xo[64 * j] = w; }
;             if (lane == 0) ss[row] = s;
;         }
.LBB0_37:
	v_readlane_b32 s26, v254, 9
	v_readlane_b32 s27, v254, 10
	v_add_co_u32_e32 v132, vcc, 0xfffff400, v4
	s_nop 1
	v_addc_co_u32_e32 v133, vcc, -1, v5, vcc
	global_load_dwordx4 v[14:17], v[132:133], off offset:-4096
	global_load_dwordx4 v[18:21], v[132:133], off offset:-3072
	global_load_dwordx4 v[22:25], v[132:133], off offset:-2048
	global_load_dwordx4 v[26:29], v[132:133], off offset:-1024
	global_load_dwordx4 v[30:33], v[132:133], off
	global_load_dwordx4 v[34:37], v[132:133], off offset:1024
	global_load_dwordx4 v[38:41], v[132:133], off offset:2048
	global_load_dwordx4 v[42:45], v[132:133], off offset:3072
	v_lshl_add_u64 v[46:47], s[26:27], 0, v[0:1]
	v_add_co_u32_e32 v46, vcc, s15, v46
	s_nop 1
	v_addc_co_u32_e32 v47, vcc, 0, v47, vcc
	s_add_u32 s18, s26, s6
	s_addc_u32 s19, s27, s7
	s_add_i32 s14, s14, s70
	s_add_u32 s6, s6, s10
	s_addc_u32 s7, s7, s11
	v_lshl_add_u64 v[0:1], v[0:1], 0, s[16:17]
	v_lshl_add_u64 v[132:133], v[132:133], 0, s[8:9]
	s_cmpk_gt_i32 s14, 0x3fff
	s_cbranch_scc1 .Lxp_tail_a
	global_load_dwordx4 v[100:103], v[132:133], off offset:-4096
	global_load_dwordx4 v[104:107], v[132:133], off offset:-3072
	global_load_dwordx4 v[108:111], v[132:133], off offset:-2048
	global_load_dwordx4 v[112:115], v[132:133], off offset:-1024
	global_load_dwordx4 v[116:119], v[132:133], off
	global_load_dwordx4 v[120:123], v[132:133], off offset:1024
	global_load_dwordx4 v[124:127], v[132:133], off offset:2048
	global_load_dwordx4 v[128:131], v[132:133], off offset:3072
	v_lshl_add_u64 v[134:135], s[26:27], 0, v[0:1]
	v_add_co_u32_e32 v134, vcc, s15, v134
	s_nop 1
	v_addc_co_u32_e32 v135, vcc, 0, v135, vcc
	s_add_u32 s22, s26, s6
	s_addc_u32 s23, s27, s7
	s_add_i32 s14, s14, s70
	s_add_u32 s6, s6, s10
	s_addc_u32 s7, s7, s11
	v_lshl_add_u64 v[0:1], v[0:1], 0, s[16:17]
	v_lshl_add_u64 v[132:133], v[132:133], 0, s[8:9]
	s_waitcnt vmcnt(8)
	v_mul_f32_e32 v136, v14, v14
	v_fmac_f32_e32 v136, v15, v15
	v_mul_f32_e32 v137, v16, v16
	v_fmac_f32_e32 v137, v17, v17
	v_add_f32_e32 v136, v136, v137
	v_mul_f32_e32 v137, v18, v18
	v_fmac_f32_e32 v137, v19, v19
	v_mul_f32_e32 v138, v20, v20
	v_fmac_f32_e32 v138, v21, v21
	v_add_f32_e32 v137, v137, v138
	v_add_f32_e32 v136, v136, v137
	v_mul_f32_e32 v137, v22, v22
	v_fmac_f32_e32 v137, v23, v23
	v_mul_f32_e32 v138, v24, v24
	v_fmac_f32_e32 v138, v25, v25
	v_add_f32_e32 v137, v137, v138
	v_add_f32_e32 v136, v136, v137
	v_mul_f32_e32 v137, v26, v26
	v_fmac_f32_e32 v137, v27, v27
	v_mul_f32_e32 v138, v28, v28
	v_fmac_f32_e32 v138, v29, v29
	v_add_f32_e32 v137, v137, v138
	v_add_f32_e32 v136, v136, v137
	v_mul_f32_e32 v137, v30, v30
	v_fmac_f32_e32 v137, v31, v31
	v_mul_f32_e32 v138, v32, v32
	v_fmac_f32_e32 v138, v33, v33
	v_add_f32_e32 v137, v137, v138
	v_add_f32_e32 v136, v136, v137
	v_mul_f32_e32 v137, v34, v34
	v_fmac_f32_e32 v137, v35, v35
	v_mul_f32_e32 v138, v36, v36
	v_fmac_f32_e32 v138, v37, v37
	v_add_f32_e32 v137, v137, v138
	v_add_f32_e32 v136, v136, v137
	v_mul_f32_e32 v137, v38, v38
	v_fmac_f32_e32 v137, v39, v39
	v_mul_f32_e32 v138, v40, v40
	v_fmac_f32_e32 v138, v41, v41
	v_add_f32_e32 v137, v137, v138
	v_add_f32_e32 v136, v136, v137
	v_mul_f32_e32 v137, v42, v42
	v_fmac_f32_e32 v137, v43, v43
	v_mul_f32_e32 v138, v44, v44
	v_fmac_f32_e32 v138, v45, v45
	v_add_f32_e32 v137, v137, v138
	v_add_f32_e32 v136, v136, v137
	ds_bpermute_b32 v137, v6, v136
	s_waitcnt lgkmcnt(0)
	v_add_f32_e32 v136, v136, v137
	ds_bpermute_b32 v137, v7, v136
	s_waitcnt lgkmcnt(0)
	v_add_f32_e32 v136, v136, v137
	ds_bpermute_b32 v137, v8, v136
	s_waitcnt lgkmcnt(0)
	v_add_f32_e32 v136, v136, v137
	ds_bpermute_b32 v137, v9, v136
	s_waitcnt lgkmcnt(0)
	v_add_f32_e32 v136, v136, v137
	ds_bpermute_b32 v137, v10, v136
	s_waitcnt lgkmcnt(0)
	v_add_f32_e32 v136, v136, v137
	ds_bpermute_b32 v137, v11, v136
	s_waitcnt lgkmcnt(0)
	v_add_f32_e32 v136, v136, v137
	v_fmamk_f32 v137, v136, 0x3a000000, v2
	v_rsq_f32_e32 v138, v137
	s_nop 0
	v_mul_f32_e32 v140, v14, v138
	v_mul_f32_e32 v141, v15, v138
	v_mul_f32_e32 v142, v16, v138
	v_mul_f32_e32 v143, v17, v138
	v_cvt_pk_bf16_f32 v144, v140, v141
	v_cvt_pk_bf16_f32 v145, v142, v143
	global_store_dwordx2 v[46:47], v[144:145], off
	v_mul_f32_e32 v146, v18, v138
	v_mul_f32_e32 v147, v19, v138
	v_mul_f32_e32 v148, v20, v138
	v_mul_f32_e32 v149, v21, v138
	v_cvt_pk_bf16_f32 v150, v146, v147
	v_cvt_pk_bf16_f32 v151, v148, v149
	global_store_dwordx2 v[46:47], v[150:151], off offset:512
	v_mul_f32_e32 v140, v22, v138
	v_mul_f32_e32 v141, v23, v138
	v_mul_f32_e32 v142, v24, v138
	v_mul_f32_e32 v143, v25, v138
	v_cvt_pk_bf16_f32 v144, v140, v141
	v_cvt_pk_bf16_f32 v145, v142, v143
	global_store_dwordx2 v[46:47], v[144:145], off offset:1024
	v_mul_f32_e32 v146, v26, v138
	v_mul_f32_e32 v147, v27, v138
	v_mul_f32_e32 v148, v28, v138
	v_mul_f32_e32 v149, v29, v138
	v_cvt_pk_bf16_f32 v150, v146, v147
	v_cvt_pk_bf16_f32 v151, v148, v149
	global_store_dwordx2 v[46:47], v[150:151], off offset:1536
	v_mul_f32_e32 v140, v30, v138
	v_mul_f32_e32 v141, v31, v138
	v_mul_f32_e32 v142, v32, v138
	v_mul_f32_e32 v143, v33, v138
	v_cvt_pk_bf16_f32 v144, v140, v141
	v_cvt_pk_bf16_f32 v145, v142, v143
	global_store_dwordx2 v[46:47], v[144:145], off offset:2048
	v_mul_f32_e32 v146, v34, v138
	v_mul_f32_e32 v147, v35, v138
	v_mul_f32_e32 v148, v36, v138
	v_mul_f32_e32 v149, v37, v138
	v_cvt_pk_bf16_f32 v150, v146, v147
	v_cvt_pk_bf16_f32 v151, v148, v149
	global_store_dwordx2 v[46:47], v[150:151], off offset:2560
	v_mul_f32_e32 v140, v38, v138
	v_mul_f32_e32 v141, v39, v138
	v_mul_f32_e32 v142, v40, v138
	v_mul_f32_e32 v143, v41, v138
	v_cvt_pk_bf16_f32 v144, v140, v141
	v_cvt_pk_bf16_f32 v145, v142, v143
	global_store_dwordx2 v[46:47], v[144:145], off offset:3072
	v_mul_f32_e32 v146, v42, v138
	v_mul_f32_e32 v147, v43, v138
	v_mul_f32_e32 v148, v44, v138
	v_mul_f32_e32 v149, v45, v138
	v_cvt_pk_bf16_f32 v150, v146, v147
	v_cvt_pk_bf16_f32 v151, v148, v149
	global_store_dwordx2 v[46:47], v[150:151], off offset:3584
	s_and_saveexec_b64 s[24:25], s[0:1]
	global_store_dword v3, v136, s[18:19]
	s_or_b64 exec, exec, s[24:25]
; #define GAS __attribute__((address_space(1)))
; __device__ __forceinline__ unsigned cvt_pk_bf16(float lo, float hi) { unsigned r; asm volatile("v_cvt_pk_bf16_f32 %0, %1, %2" : "=v"(r) : "v"(lo), "v"(hi)); return r; }
; __global__ void __launch_bounds__(NTHREADS, 2) mk_fwd(Args args) {
;     ...
;         for (int row = gw; row < MT; row += ngw) {
;             const GAS f32x4* xr = (const GAS f32x4*)(x + (size_t)row * DM) + lane; u32x2* xo = (u32x2*)(R1 + (size_t)row * DM) + lane;
;             float s = 0.f; f32x4 xv[8];
; #pragma unroll
;             for (int j = 0; j < 8; ++j) { xv[j] = xr[64 * j]; s += (xv[j][0] * xv[j][0] + xv[j][1] * xv[j][1]) + (xv[j][2] * xv[j][2] + xv[j][3] * xv[j][3]); }
;             s = wave_sum(s);
;             const float rs0 = __builtin_amdgcn_rsqf(s * (1.0f / DM) + RMS_EPS);
; #pragma unroll
;             for (int j = 0; j < 8; ++j) { const f32x4 v = xv[j] * rs0; u32x2 w; w.x = cvt_pk_bf16(v[0], v[1]); w.y = cvt_pk_bf16(v[2], v[3]); xo[64 * j] = w; }
;             if (lane == 0) ss[row] = s;
;         }
.Lxp_loop:
	s_cmpk_gt_i32 s14, 0x3fff
	s_cbranch_scc1 .Lxp_tail_b
	global_load_dwordx4 v[14:17], v[132:133], off offset:-4096
	global_load_dwordx4 v[18:21], v[132:133], off offset:-3072
	global_load_dwordx4 v[22:25], v[132:133], off offset:-2048
	global_load_dwordx4 v[26:29], v[132:133], off offset:-1024
	global_load_dwordx4 v[30:33], v[132:133], off
	global_load_dwordx4 v[34:37], v[132:133], off offset:1024
	global_load_dwordx4 v[38:41], v[132:133], off offset:2048
	global_load_dwordx4 v[42:45], v[132:133], off offset:3072
	v_lshl_add_u64 v[46:47], s[26:27], 0, v[0:1]
	v_add_co_u32_e32 v46, vcc, s15, v46
	s_nop 1
	v_addc_co_u32_e32 v47, vcc, 0, v47, vcc
	s_add_u32 s18, s26, s6
	s_addc_u32 s19, s27, s7
	s_add_i32 s14, s14, s70
	s_add_u32 s6, s6, s10
	s_addc_u32 s7, s7, s11
	v_lshl_add_u64 v[0:1], v[0:1], 0, s[16:17]
	v_lshl_add_u64 v[132:133], v[132:133], 0, s[8:9]
	s_waitcnt vmcnt(16)
	v_mul_f32_e32 v136, v100, v100
	v_fmac_f32_e32 v136, v101, v101
	v_mul_f32_e32 v137, v102, v102
	v_fmac_f32_e32 v137, v103, v103
	v_add_f32_e32 v136, v136, v137
	v_mul_f32_e32 v137, v104, v104
	v_fmac_f32_e32 v137, v105, v105
	v_mul_f32_e32 v138, v106, v106
	v_fmac_f32_e32 v138, v107, v107
	v_add_f32_e32 v137, v137, v138
	v_add_f32_e32 v136, v136, v137
	v_mul_f32_e32 v137, v108, v108
	v_fmac_f32_e32 v137, v109, v109
	v_mul_f32_e32 v138, v110, v110
	v_fmac_f32_e32 v138, v111, v111
	v_add_f32_e32 v137, v137, v138
	v_add_f32_e32 v136, v136, v137
	v_mul_f32_e32 v137, v112, v112
	v_fmac_f32_e32 v137, v113, v113
	v_mul_f32_e32 v138, v114, v114
	v_fmac_f32_e32 v138, v115, v115
	v_add_f32_e32 v137, v137, v138
	v_add_f32_e32 v136, v136, v137
	v_mul_f32_e32 v137, v116, v116
	v_fmac_f32_e32 v137, v117, v117
	v_mul_f32_e32 v138, v118, v118
	v_fmac_f32_e32 v138, v119, v119
	v_add_f32_e32 v137, v137, v138
	v_add_f32_e32 v136, v136, v137
	v_mul_f32_e32 v137, v120, v120
	v_fmac_f32_e32 v137, v121, v121
	v_mul_f32_e32 v138, v122, v122
	v_fmac_f32_e32 v138, v123, v123
	v_add_f32_e32 v137, v137, v138
	v_add_f32_e32 v136, v136, v137
	v_mul_f32_e32 v137, v124, v124
	v_fmac_f32_e32 v137, v125, v125
	v_mul_f32_e32 v138, v126, v126
	v_fmac_f32_e32 v138, v127, v127
	v_add_f32_e32 v137, v137, v138
	v_add_f32_e32 v136, v136, v137
	v_mul_f32_e32 v137, v128, v128
	v_fmac_f32_e32 v137, v129, v129
	v_mul_f32_e32 v138, v130, v130
	v_fmac_f32_e32 v138, v131, v131
	v_add_f32_e32 v137, v137, v138
	v_add_f32_e32 v136, v136, v137
	ds_bpermute_b32 v137, v6, v136
	s_waitcnt lgkmcnt(0)
	v_add_f32_e32 v136, v136, v137
	ds_bpermute_b32 v137, v7, v136
	s_waitcnt lgkmcnt(0)
	v_add_f32_e32 v136, v136, v137
	ds_bpermute_b32 v137, v8, v136
	s_waitcnt lgkmcnt(0)
	v_add_f32_e32 v136, v136, v137
	ds_bpermute_b32 v137, v9, v136
	s_waitcnt lgkmcnt(0)
	v_add_f32_e32 v136, v136, v137
	ds_bpermute_b32 v137, v10, v136
	s_waitcnt lgkmcnt(0)
	v_add_f32_e32 v136, v136, v137
	ds_bpermute_b32 v137, v11, v136
	s_waitcnt lgkmcnt(0)
	v_add_f32_e32 v136, v136, v137
	v_fmamk_f32 v137, v136, 0x3a000000, v2
	v_rsq_f32_e32 v138, v137
	s_nop 0
	v_mul_f32_e32 v140, v100, v138
	v_mul_f32_e32 v141, v101, v138
	v_mul_f32_e32 v142, v102, v138
	v_mul_f32_e32 v143, v103, v138
	v_cvt_pk_bf16_f32 v144, v140, v141
	v_cvt_pk_bf16_f32 v145, v142, v143
	global_store_dwordx2 v[134:135], v[144:145], off
	v_mul_f32_e32 v146, v104, v138
	v_mul_f32_e32 v147, v105, v138
	v_mul_f32_e32 v148, v106, v138
	v_mul_f32_e32 v149, v107, v138
	v_cvt_pk_bf16_f32 v150, v146, v147
	v_cvt_pk_bf16_f32 v151, v148, v149
	global_store_dwordx2 v[134:135], v[150:151], off offset:512
	v_mul_f32_e32 v140, v108, v138
	v_mul_f32_e32 v141, v109, v138
	v_mul_f32_e32 v142, v110, v138
	v_mul_f32_e32 v143, v111, v138
	v_cvt_pk_bf16_f32 v144, v140, v141
	v_cvt_pk_bf16_f32 v145, v142, v143
	global_store_dwordx2 v[134:135], v[144:145], off offset:1024
	v_mul_f32_e32 v146, v112, v138
	v_mul_f32_e32 v147, v113, v138
	v_mul_f32_e32 v148, v114, v138
	v_mul_f32_e32 v149, v115, v138
	v_cvt_pk_bf16_f32 v150, v146, v147
	v_cvt_pk_bf16_f32 v151, v148, v149
	global_store_dwordx2 v[134:135], v[150:151], off offset:1536
	v_mul_f32_e32 v140, v116, v138
	v_mul_f32_e32 v141, v117, v138
	v_mul_f32_e32 v142, v118, v138
	v_mul_f32_e32 v143, v119, v138
	v_cvt_pk_bf16_f32 v144, v140, v141
	v_cvt_pk_bf16_f32 v145, v142, v143
	global_store_dwordx2 v[134:135], v[144:145], off offset:2048
	v_mul_f32_e32 v146, v120, v138
	v_mul_f32_e32 v147, v121, v138
	v_mul_f32_e32 v148, v122, v138
	v_mul_f32_e32 v149, v123, v138
	v_cvt_pk_bf16_f32 v150, v146, v147
	v_cvt_pk_bf16_f32 v151, v148, v149
	global_store_dwordx2 v[134:135], v[150:151], off offset:2560
	v_mul_f32_e32 v140, v124, v138
	v_mul_f32_e32 v141, v125, v138
	v_mul_f32_e32 v142, v126, v138
	v_mul_f32_e32 v143, v127, v138
	v_cvt_pk_bf16_f32 v144, v140, v141
	v_cvt_pk_bf16_f32 v145, v142, v143
	global_store_dwordx2 v[134:135], v[144:145], off offset:3072
	v_mul_f32_e32 v146, v128, v138
	v_mul_f32_e32 v147, v129, v138
	v_mul_f32_e32 v148, v130, v138
	v_mul_f32_e32 v149, v131, v138
	v_cvt_pk_bf16_f32 v150, v146, v147
	v_cvt_pk_bf16_f32 v151, v148, v149
	global_store_dwordx2 v[134:135], v[150:151], off offset:3584
	s_and_saveexec_b64 s[24:25], s[0:1]
	global_store_dword v3, v136, s[22:23]
	s_or_b64 exec, exec, s[24:25]
	s_cmpk_gt_i32 s14, 0x3fff
	s_cbranch_scc1 .Lxp_tail_a
; #define GAS __attribute__((address_space(1)))
; __device__ __forceinline__ unsigned cvt_pk_bf16(float lo, float hi) { unsigned r; asm volatile("v_cvt_pk_bf16_f32 %0, %1, %2" : "=v"(r) : "v"(lo), "v"(hi)); return r; }
; __global__ void __launch_bounds__(NTHREADS, 2) mk_fwd(Args args) {
;     ...
;         for (int row = gw; row < MT; row += ngw) {
;             const GAS f32x4* xr = (const GAS f32x4*)(x + (size_t)row * DM) + lane; u32x2* xo = (u32x2*)(R1 + (size_t)row * DM) + lane;
;             float s = 0.f; f32x4 xv[8];
; #pragma unroll
;             for (int j = 0; j < 8; ++j) { xv[j] = xr[64 * j]; s += (xv[j][0] * xv[j][0] + xv[j][1] * xv[j][1]) + (xv[j][2] * xv[j][2] + xv[j][3] * xv[j][3]); }
;             s = wave_sum(s);
;             const float rs0 = __builtin_amdgcn_rsqf(s * (1.0f / DM) + RMS_EPS);
; #pragma unroll
;             for (int j = 0; j < 8; ++j) { const f32x4 v = xv[j] * rs0; u32x2 w; w.x = cvt_pk_bf16(v[0], v[1]); w.y = cvt_pk_bf16(v[2], v[3]); xo[64 * j] = w; }
;             if (lane == 0) ss[row] = s;
;         }
	global_load_dwordx4 v[100:103], v[132:133], off offset:-4096
	global_load_dwordx4 v[104:107], v[132:133], off offset:-3072
	global_load_dwordx4 v[108:111], v[132:133], off offset:-2048
	global_load_dwordx4 v[112:115], v[132:133], off offset:-1024
	global_load_dwordx4 v[116:119], v[132:133], off
	global_load_dwordx4 v[120:123], v[132:133], off offset:1024
	global_load_dwordx4 v[124:127], v[132:133], off offset:2048
	global_load_dwordx4 v[128:131], v[132:133], off offset:3072
	v_lshl_add_u64 v[134:135], s[26:27], 0, v[0:1]
	v_add_co_u32_e32 v134, vcc, s15, v134
	s_nop 1
	v_addc_co_u32_e32 v135, vcc, 0, v135, vcc
	s_add_u32 s22, s26, s6
	s_addc_u32 s23, s27, s7
	s_add_i32 s14, s14, s70
	s_add_u32 s6, s6, s10
	s_addc_u32 s7, s7, s11
	v_lshl_add_u64 v[0:1], v[0:1], 0, s[16:17]
	v_lshl_add_u64 v[132:133], v[132:133], 0, s[8:9]
	s_waitcnt vmcnt(16)
	v_mul_f32_e32 v136, v14, v14
	v_fmac_f32_e32 v136, v15, v15
	v_mul_f32_e32 v137, v16, v16
	v_fmac_f32_e32 v137, v17, v17
	v_add_f32_e32 v136, v136, v137
	v_mul_f32_e32 v137, v18, v18
	v_fmac_f32_e32 v137, v19, v19
	v_mul_f32_e32 v138, v20, v20
	v_fmac_f32_e32 v138, v21, v21
	v_add_f32_e32 v137, v137, v138
	v_add_f32_e32 v136, v136, v137
	v_mul_f32_e32 v137, v22, v22
	v_fmac_f32_e32 v137, v23, v23
	v_mul_f32_e32 v138, v24, v24
	v_fmac_f32_e32 v138, v25, v25
	v_add_f32_e32 v137, v137, v138
	v_add_f32_e32 v136, v136, v137
	v_mul_f32_e32 v137, v26, v26
	v_fmac_f32_e32 v137, v27, v27
	v_mul_f32_e32 v138, v28, v28
	v_fmac_f32_e32 v138, v29, v29
	v_add_f32_e32 v137, v137, v138
	v_add_f32_e32 v136, v136, v137
	v_mul_f32_e32 v137, v30, v30
	v_fmac_f32_e32 v137, v31, v31
	v_mul_f32_e32 v138, v32, v32
	v_fmac_f32_e32 v138, v33, v33
	v_add_f32_e32 v137, v137, v138
	v_add_f32_e32 v136, v136, v137
	v_mul_f32_e32 v137, v34, v34
	v_fmac_f32_e32 v137, v35, v35
	v_mul_f32_e32 v138, v36, v36
	v_fmac_f32_e32 v138, v37, v37
	v_add_f32_e32 v137, v137, v138
	v_add_f32_e32 v136, v136, v137
	v_mul_f32_e32 v137, v38, v38
	v_fmac_f32_e32 v137, v39, v39
	v_mul_f32_e32 v138, v40, v40
	v_fmac_f32_e32 v138, v41, v41
	v_add_f32_e32 v137, v137, v138
	v_add_f32_e32 v136, v136, v137
	v_mul_f32_e32 v137, v42, v42
	v_fmac_f32_e32 v137, v43, v43
	v_mul_f32_e32 v138, v44, v44
	v_fmac_f32_e32 v138, v45, v45
	v_add_f32_e32 v137, v137, v138
	v_add_f32_e32 v136, v136, v137
	ds_bpermute_b32 v137, v6, v136
	s_waitcnt lgkmcnt(0)
	v_add_f32_e32 v136, v136, v137
	ds_bpermute_b32 v137, v7, v136
	s_waitcnt lgkmcnt(0)
	v_add_f32_e32 v136, v136, v137
	ds_bpermute_b32 v137, v8, v136
	s_waitcnt lgkmcnt(0)
	v_add_f32_e32 v136, v136, v137
	ds_bpermute_b32 v137, v9, v136
	s_waitcnt lgkmcnt(0)
	v_add_f32_e32 v136, v136, v137
	ds_bpermute_b32 v137, v10, v136
	s_waitcnt lgkmcnt(0)
	v_add_f32_e32 v136, v136, v137
	ds_bpermute_b32 v137, v11, v136
	s_waitcnt lgkmcnt(0)
	v_add_f32_e32 v136, v136, v137
	v_fmamk_f32 v137, v136, 0x3a000000, v2
	v_rsq_f32_e32 v138, v137
	s_nop 0
	v_mul_f32_e32 v140, v14, v138
	v_mul_f32_e32 v141, v15, v138
	v_mul_f32_e32 v142, v16, v138
	v_mul_f32_e32 v143, v17, v138
	v_cvt_pk_bf16_f32 v144, v140, v141
	v_cvt_pk_bf16_f32 v145, v142, v143
	global_store_dwordx2 v[46:47], v[144:145], off
	v_mul_f32_e32 v146, v18, v138
	v_mul_f32_e32 v147, v19, v138
	v_mul_f32_e32 v148, v20, v138
	v_mul_f32_e32 v149, v21, v138
	v_cvt_pk_bf16_f32 v150, v146, v147
	v_cvt_pk_bf16_f32 v151, v148, v149
	global_store_dwordx2 v[46:47], v[150:151], off offset:512
	v_mul_f32_e32 v140, v22, v138
	v_mul_f32_e32 v141, v23, v138
	v_mul_f32_e32 v142, v24, v138
	v_mul_f32_e32 v143, v25, v138
	v_cvt_pk_bf16_f32 v144, v140, v141
	v_cvt_pk_bf16_f32 v145, v142, v143
	global_store_dwordx2 v[46:47], v[144:145], off offset:1024
	v_mul_f32_e32 v146, v26, v138
	v_mul_f32_e32 v147, v27, v138
	v_mul_f32_e32 v148, v28, v138
	v_mul_f32_e32 v149, v29, v138
	v_cvt_pk_bf16_f32 v150, v146, v147
	v_cvt_pk_bf16_f32 v151, v148, v149
	global_store_dwordx2 v[46:47], v[150:151], off offset:1536
	v_mul_f32_e32 v140, v30, v138
	v_mul_f32_e32 v141, v31, v138
	v_mul_f32_e32 v142, v32, v138
	v_mul_f32_e32 v143, v33, v138
	v_cvt_pk_bf16_f32 v144, v140, v141
	v_cvt_pk_bf16_f32 v145, v142, v143
	global_store_dwordx2 v[46:47], v[144:145], off offset:2048
	v_mul_f32_e32 v146, v34, v138
	v_mul_f32_e32 v147, v35, v138
	v_mul_f32_e32 v148, v36, v138
	v_mul_f32_e32 v149, v37, v138
	v_cvt_pk_bf16_f32 v150, v146, v147
	v_cvt_pk_bf16_f32 v151, v148, v149
	global_store_dwordx2 v[46:47], v[150:151], off offset:2560
	v_mul_f32_e32 v140, v38, v138
	v_mul_f32_e32 v141, v39, v138
	v_mul_f32_e32 v142, v40, v138
	v_mul_f32_e32 v143, v41, v138
	v_cvt_pk_bf16_f32 v144, v140, v141
	v_cvt_pk_bf16_f32 v145, v142, v143
	global_store_dwordx2 v[46:47], v[144:145], off offset:3072
	v_mul_f32_e32 v146, v42, v138
	v_mul_f32_e32 v147, v43, v138
	v_mul_f32_e32 v148, v44, v138
	v_mul_f32_e32 v149, v45, v138
	v_cvt_pk_bf16_f32 v150, v146, v147
	v_cvt_pk_bf16_f32 v151, v148, v149
	global_store_dwordx2 v[46:47], v[150:151], off offset:3584
	s_and_saveexec_b64 s[24:25], s[0:1]
	global_store_dword v3, v136, s[18:19]
	s_or_b64 exec, exec, s[24:25]
	s_branch .Lxp_loop
; #define GAS __attribute__((address_space(1)))
; __device__ __forceinline__ unsigned cvt_pk_bf16(float lo, float hi) { unsigned r; asm volatile("v_cvt_pk_bf16_f32 %0, %1, %2" : "=v"(r) : "v"(lo), "v"(hi)); return r; }
; __global__ void __launch_bounds__(NTHREADS, 2) mk_fwd(Args args) {
;     ...
;         for (int row = gw; row < MT; row += ngw) {
;             const GAS f32x4* xr = (const GAS f32x4*)(x + (size_t)row * DM) + lane; u32x2* xo = (u32x2*)(R1 + (size_t)row * DM) + lane;
;             float s = 0.f; f32x4 xv[8];
; #pragma unroll
;             for (int j = 0; j < 8; ++j) { xv[j] = xr[64 * j]; s += (xv[j][0] * xv[j][0] + xv[j][1] * xv[j][1]) + (xv[j][2] * xv[j][2] + xv[j][3] * xv[j][3]); }
;             s = wave_sum(s);
;             const float rs0 = __builtin_amdgcn_rsqf(s * (1.0f / DM) + RMS_EPS);
; #pragma unroll
;             for (int j = 0; j < 8; ++j) { const f32x4 v = xv[j] * rs0; u32x2 w; w.x = cvt_pk_bf16(v[0], v[1]); w.y = cvt_pk_bf16(v[2], v[3]); xo[64 * j] = w; }
;             if (lane == 0) ss[row] = s;
;         }
.Lxp_tail_a:
	s_waitcnt vmcnt(0)
	v_mul_f32_e32 v136, v14, v14
	v_fmac_f32_e32 v136, v15, v15
	v_mul_f32_e32 v137, v16, v16
	v_fmac_f32_e32 v137, v17, v17
	v_add_f32_e32 v136, v136, v137
	v_mul_f32_e32 v137, v18, v18
	v_fmac_f32_e32 v137, v19, v19
	v_mul_f32_e32 v138, v20, v20
	v_fmac_f32_e32 v138, v21, v21
	v_add_f32_e32 v137, v137, v138
	v_add_f32_e32 v136, v136, v137
	v_mul_f32_e32 v137, v22, v22
	v_fmac_f32_e32 v137, v23, v23
	v_mul_f32_e32 v138, v24, v24
	v_fmac_f32_e32 v138, v25, v25
	v_add_f32_e32 v137, v137, v138
	v_add_f32_e32 v136, v136, v137
	v_mul_f32_e32 v137, v26, v26
	v_fmac_f32_e32 v137, v27, v27
	v_mul_f32_e32 v138, v28, v28
	v_fmac_f32_e32 v138, v29, v29
	v_add_f32_e32 v137, v137, v138
	v_add_f32_e32 v136, v136, v137
	v_mul_f32_e32 v137, v30, v30
	v_fmac_f32_e32 v137, v31, v31
	v_mul_f32_e32 v138, v32, v32
	v_fmac_f32_e32 v138, v33, v33
	v_add_f32_e32 v137, v137, v138
	v_add_f32_e32 v136, v136, v137
	v_mul_f32_e32 v137, v34, v34
	v_fmac_f32_e32 v137, v35, v35
	v_mul_f32_e32 v138, v36, v36
	v_fmac_f32_e32 v138, v37, v37
	v_add_f32_e32 v137, v137, v138
	v_add_f32_e32 v136, v136, v137
	v_mul_f32_e32 v137, v38, v38
	v_fmac_f32_e32 v137, v39, v39
	v_mul_f32_e32 v138, v40, v40
	v_fmac_f32_e32 v138, v41, v41
	v_add_f32_e32 v137, v137, v138
	v_add_f32_e32 v136, v136, v137
	v_mul_f32_e32 v137, v42, v42
	v_fmac_f32_e32 v137, v43, v43
	v_mul_f32_e32 v138, v44, v44
	v_fmac_f32_e32 v138, v45, v45
	v_add_f32_e32 v137, v137, v138
	v_add_f32_e32 v136, v136, v137
	ds_bpermute_b32 v137, v6, v136
	s_waitcnt lgkmcnt(0)
	v_add_f32_e32 v136, v136, v137
	ds_bpermute_b32 v137, v7, v136
	s_waitcnt lgkmcnt(0)
	v_add_f32_e32 v136, v136, v137
	ds_bpermute_b32 v137, v8, v136
	s_waitcnt lgkmcnt(0)
	v_add_f32_e32 v136, v136, v137
	ds_bpermute_b32 v137, v9, v136
	s_waitcnt lgkmcnt(0)
	v_add_f32_e32 v136, v136, v137
	ds_bpermute_b32 v137, v10, v136
	s_waitcnt lgkmcnt(0)
	v_add_f32_e32 v136, v136, v137
	ds_bpermute_b32 v137, v11, v136
	s_waitcnt lgkmcnt(0)
	v_add_f32_e32 v136, v136, v137
	v_fmamk_f32 v137, v136, 0x3a000000, v2
	v_rsq_f32_e32 v138, v137
	s_nop 0
	v_mul_f32_e32 v140, v14, v138
	v_mul_f32_e32 v141, v15, v138
	v_mul_f32_e32 v142, v16, v138
	v_mul_f32_e32 v143, v17, v138
	v_cvt_pk_bf16_f32 v144, v140, v141
	v_cvt_pk_bf16_f32 v145, v142, v143
	global_store_dwordx2 v[46:47], v[144:145], off
	v_mul_f32_e32 v146, v18, v138
	v_mul_f32_e32 v147, v19, v138
	v_mul_f32_e32 v148, v20, v138
	v_mul_f32_e32 v149, v21, v138
	v_cvt_pk_bf16_f32 v150, v146, v147
	v_cvt_pk_bf16_f32 v151, v148, v149
	global_store_dwordx2 v[46:47], v[150:151], off offset:512
	v_mul_f32_e32 v140, v22, v138
	v_mul_f32_e32 v141, v23, v138
	v_mul_f32_e32 v142, v24, v138
	v_mul_f32_e32 v143, v25, v138
	v_cvt_pk_bf16_f32 v144, v140, v141
	v_cvt_pk_bf16_f32 v145, v142, v143
	global_store_dwordx2 v[46:47], v[144:145], off offset:1024
	v_mul_f32_e32 v146, v26, v138
	v_mul_f32_e32 v147, v27, v138
	v_mul_f32_e32 v148, v28, v138
	v_mul_f32_e32 v149, v29, v138
	v_cvt_pk_bf16_f32 v150, v146, v147
	v_cvt_pk_bf16_f32 v151, v148, v149
	global_store_dwordx2 v[46:47], v[150:151], off offset:1536
	v_mul_f32_e32 v140, v30, v138
	v_mul_f32_e32 v141, v31, v138
	v_mul_f32_e32 v142, v32, v138
	v_mul_f32_e32 v143, v33, v138
	v_cvt_pk_bf16_f32 v144, v140, v141
	v_cvt_pk_bf16_f32 v145, v142, v143
	global_store_dwordx2 v[46:47], v[144:145], off offset:2048
	v_mul_f32_e32 v146, v34, v138
	v_mul_f32_e32 v147, v35, v138
	v_mul_f32_e32 v148, v36, v138
	v_mul_f32_e32 v149, v37, v138
	v_cvt_pk_bf16_f32 v150, v146, v147
	v_cvt_pk_bf16_f32 v151, v148, v149
	global_store_dwordx2 v[46:47], v[150:151], off offset:2560
	v_mul_f32_e32 v140, v38, v138
	v_mul_f32_e32 v141, v39, v138
	v_mul_f32_e32 v142, v40, v138
	v_mul_f32_e32 v143, v41, v138
	v_cvt_pk_bf16_f32 v144, v140, v141
	v_cvt_pk_bf16_f32 v145, v142, v143
	global_store_dwordx2 v[46:47], v[144:145], off offset:3072
	v_mul_f32_e32 v146, v42, v138
	v_mul_f32_e32 v147, v43, v138
	v_mul_f32_e32 v148, v44, v138
	v_mul_f32_e32 v149, v45, v138
	v_cvt_pk_bf16_f32 v150, v146, v147
	v_cvt_pk_bf16_f32 v151, v148, v149
	global_store_dwordx2 v[46:47], v[150:151], off offset:3584
	s_and_saveexec_b64 s[24:25], s[0:1]
	global_store_dword v3, v136, s[18:19]
	s_or_b64 exec, exec, s[24:25]
	s_branch .LBB0_39
; #define GAS __attribute__((address_space(1)))
; __device__ __forceinline__ unsigned cvt_pk_bf16(float lo, float hi) { unsigned r; asm volatile("v_cvt_pk_bf16_f32 %0, %1, %2" : "=v"(r) : "v"(lo), "v"(hi)); return r; }
; __global__ void __launch_bounds__(NTHREADS, 2) mk_fwd(Args args) {
;     ...
;         for (int row = gw; row < MT; row += ngw) {
;             const GAS f32x4* xr = (const GAS f32x4*)(x + (size_t)row * DM) + lane; u32x2* xo = (u32x2*)(R1 + (size_t)row * DM) + lane;
;             float s = 0.f; f32x4 xv[8];
; #pragma unroll
;             for (int j = 0; j < 8; ++j) { xv[j] = xr[64 * j]; s += (xv[j][0] * xv[j][0] + xv[j][1] * xv[j][1]) + (xv[j][2] * xv[j][2] + xv[j][3] * xv[j][3]); }
;             s = wave_sum(s);
;             const float rs0 = __builtin_amdgcn_rsqf(s * (1.0f / DM) + RMS_EPS);
; #pragma unroll
;             for (int j = 0; j < 8; ++j) { const f32x4 v = xv[j] * rs0; u32x2 w; w.x = cvt_pk_bf16(v[0], v[1]); w.y = cvt_pk_bf16(v[2], v[3]); xo[64 * j] = w; }
;             if (lane == 0) ss[row] = s;
;         }
.Lxp_tail_b:
	s_waitcnt vmcnt(0)
	v_mul_f32_e32 v136, v100, v100
	v_fmac_f32_e32 v136, v101, v101
	v_mul_f32_e32 v137, v102, v102
	v_fmac_f32_e32 v137, v103, v103
	v_add_f32_e32 v136, v136, v137
	v_mul_f32_e32 v137, v104, v104
	v_fmac_f32_e32 v137, v105, v105
	v_mul_f32_e32 v138, v106, v106
	v_fmac_f32_e32 v138, v107, v107
	v_add_f32_e32 v137, v137, v138
	v_add_f32_e32 v136, v136, v137
	v_mul_f32_e32 v137, v108, v108
	v_fmac_f32_e32 v137, v109, v109
	v_mul_f32_e32 v138, v110, v110
	v_fmac_f32_e32 v138, v111, v111
	v_add_f32_e32 v137, v137, v138
	v_add_f32_e32 v136, v136, v137
	v_mul_f32_e32 v137, v112, v112
	v_fmac_f32_e32 v137, v113, v113
	v_mul_f32_e32 v138, v114, v114
	v_fmac_f32_e32 v138, v115, v115
	v_add_f32_e32 v137, v137, v138
	v_add_f32_e32 v136, v136, v137
	v_mul_f32_e32 v137, v116, v116
	v_fmac_f32_e32 v137, v117, v117
	v_mul_f32_e32 v138, v118, v118
	v_fmac_f32_e32 v138, v119, v119
	v_add_f32_e32 v137, v137, v138
	v_add_f32_e32 v136, v136, v137
	v_mul_f32_e32 v137, v120, v120
	v_fmac_f32_e32 v137, v121, v121
	v_mul_f32_e32 v138, v122, v122
	v_fmac_f32_e32 v138, v123, v123
	v_add_f32_e32 v137, v137, v138
	v_add_f32_e32 v136, v136, v137
	v_mul_f32_e32 v137, v124, v124
	v_fmac_f32_e32 v137, v125, v125
	v_mul_f32_e32 v138, v126, v126
	v_fmac_f32_e32 v138, v127, v127
	v_add_f32_e32 v137, v137, v138
	v_add_f32_e32 v136, v136, v137
	v_mul_f32_e32 v137, v128, v128
	v_fmac_f32_e32 v137, v129, v129
	v_mul_f32_e32 v138, v130, v130
	v_fmac_f32_e32 v138, v131, v131
	v_add_f32_e32 v137, v137, v138
	v_add_f32_e32 v136, v136, v137
	ds_bpermute_b32 v137, v6, v136
	s_waitcnt lgkmcnt(0)
	v_add_f32_e32 v136, v136, v137
	ds_bpermute_b32 v137, v7, v136
	s_waitcnt lgkmcnt(0)
	v_add_f32_e32 v136, v136, v137
	ds_bpermute_b32 v137, v8, v136
	s_waitcnt lgkmcnt(0)
	v_add_f32_e32 v136, v136, v137
	ds_bpermute_b32 v137, v9, v136
	s_waitcnt lgkmcnt(0)
	v_add_f32_e32 v136, v136, v137
	ds_bpermute_b32 v137, v10, v136
	s_waitcnt lgkmcnt(0)
	v_add_f32_e32 v136, v136, v137
	ds_bpermute_b32 v137, v11, v136
	s_waitcnt lgkmcnt(0)
	v_add_f32_e32 v136, v136, v137
	v_fmamk_f32 v137, v136, 0x3a000000, v2
	v_rsq_f32_e32 v138, v137
	s_nop 0
	v_mul_f32_e32 v140, v100, v138
	v_mul_f32_e32 v141, v101, v138
	v_mul_f32_e32 v142, v102, v138
	v_mul_f32_e32 v143, v103, v138
	v_cvt_pk_bf16_f32 v144, v140, v141
	v_cvt_pk_bf16_f32 v145, v142, v143
	global_store_dwordx2 v[134:135], v[144:145], off
	v_mul_f32_e32 v146, v104, v138
	v_mul_f32_e32 v147, v105, v138
	v_mul_f32_e32 v148, v106, v138
	v_mul_f32_e32 v149, v107, v138
	v_cvt_pk_bf16_f32 v150, v146, v147
	v_cvt_pk_bf16_f32 v151, v148, v149
	global_store_dwordx2 v[134:135], v[150:151], off offset:512
	v_mul_f32_e32 v140, v108, v138
	v_mul_f32_e32 v141, v109, v138
	v_mul_f32_e32 v142, v110, v138
	v_mul_f32_e32 v143, v111, v138
	v_cvt_pk_bf16_f32 v144, v140, v141
	v_cvt_pk_bf16_f32 v145, v142, v143
	global_store_dwordx2 v[134:135], v[144:145], off offset:1024
	v_mul_f32_e32 v146, v112, v138
	v_mul_f32_e32 v147, v113, v138
	v_mul_f32_e32 v148, v114, v138
	v_mul_f32_e32 v149, v115, v138
	v_cvt_pk_bf16_f32 v150, v146, v147
	v_cvt_pk_bf16_f32 v151, v148, v149
	global_store_dwordx2 v[134:135], v[150:151], off offset:1536
	v_mul_f32_e32 v140, v116, v138
	v_mul_f32_e32 v141, v117, v138
	v_mul_f32_e32 v142, v118, v138
	v_mul_f32_e32 v143, v119, v138
	v_cvt_pk_bf16_f32 v144, v140, v141
	v_cvt_pk_bf16_f32 v145, v142, v143
	global_store_dwordx2 v[134:135], v[144:145], off offset:2048
	v_mul_f32_e32 v146, v120, v138
	v_mul_f32_e32 v147, v121, v138
	v_mul_f32_e32 v148, v122, v138
	v_mul_f32_e32 v149, v123, v138
	v_cvt_pk_bf16_f32 v150, v146, v147
	v_cvt_pk_bf16_f32 v151, v148, v149
	global_store_dwordx2 v[134:135], v[150:151], off offset:2560
	v_mul_f32_e32 v140, v124, v138
	v_mul_f32_e32 v141, v125, v138
	v_mul_f32_e32 v142, v126, v138
	v_mul_f32_e32 v143, v127, v138
	v_cvt_pk_bf16_f32 v144, v140, v141
	v_cvt_pk_bf16_f32 v145, v142, v143
	global_store_dwordx2 v[134:135], v[144:145], off offset:3072
	v_mul_f32_e32 v146, v128, v138
	v_mul_f32_e32 v147, v129, v138
	v_mul_f32_e32 v148, v130, v138
	v_mul_f32_e32 v149, v131, v138
	v_cvt_pk_bf16_f32 v150, v146, v147
	v_cvt_pk_bf16_f32 v151, v148, v149
	global_store_dwordx2 v[134:135], v[150:151], off offset:3584
	s_and_saveexec_b64 s[24:25], s[0:1]
	global_store_dword v3, v136, s[22:23]
	s_or_b64 exec, exec, s[24:25]
